# static priority raise (s_setprio 3) for the scan waves during the S5 scan phase, reset to 0 at its end
# speedup vs baseline: 1.0077x; 1.0027x over previous
.LBB0_560:
	s_or_b64 exec, exec, s[0:1]
	v_mov_b32_e32 v172, v194
	s_waitcnt lgkmcnt(0)
	s_barrier
	s_nop 0
	v_readfirstlane_b32 s0, v172
	s_ashr_i32 s3, s0, 6
	v_and_b32_e32 v173, 63, v172
	s_cmp_lt_i32 s3, 4
	s_mov_b64 s[0:1], -1
	s_cbranch_scc0 .LBB0_567
	s_lshl_b32 s0, s65, 2
	s_add_i32 s6, s3, s0
	s_cmpk_gt_i32 s6, 0x3ff
	s_cbranch_scc1 .LBB0_566
	s_setprio 3
	v_lshrrev_b32_e32 v1, 5, v173
	s_mul_i32 s1, s3, 0x6a00
	v_lshlrev_b32_e32 v2, 5, v172
	s_add_i32 s1, s1, 0
	v_and_b32_e32 v177, 0x1e0, v2
	v_lshlrev_b32_e32 v2, 4, v1
	v_and_b32_e32 v174, 31, v172
	v_lshlrev_b32_e32 v175, 3, v1
	v_lshlrev_b32_e32 v176, 2, v1
	v_add_u32_e32 v6, s1, v2
	s_movk_i32 s2, 0x90
	v_mov_b32_e32 v1, s1
	s_movk_i32 s1, 0x110
	v_mad_u32_u24 v178, v173, s2, v1
	v_mad_u32_u24 v8, v174, s1, v1
	s_lshl_b32 s1, s65, 5
	s_lshl_b32 s2, s3, 3
	v_mov_b32_e32 v133, 0
	s_add_i32 s10, s1, s2
	s_lshl_b32 s1, s3, 4
	v_mov_b32_e32 v3, v133
	s_and_b32 s1, s1, 16
	v_lshrrev_b32_e32 v1, 3, v172
	v_lshl_add_u64 v[138:139], s[44:45], 0, v[2:3]
	v_lshl_add_u64 v[140:141], s[46:47], 0, v[2:3]
	v_lshl_add_u64 v[142:143], s[48:49], 0, v[2:3]
	v_or_b32_e32 v3, s1, v176
	v_lshlrev_b32_e32 v0, 6, v172
	v_and_b32_e32 v179, 2, v1
	v_lshlrev_b32_e32 v1, 1, v172
	v_and_b32_e32 v132, 32, v173
	v_lshlrev_b32_e32 v3, 1, v3
	v_and_b32_e32 v0, 0x3c0, v0
	v_and_b32_e32 v181, 16, v1
	v_lshl_add_u64 v[134:135], s[40:41], 0, v[132:133]
	v_lshl_add_u64 v[136:137], s[42:43], 0, v[132:133]
	v_mov_b32_e32 v1, v133
	v_or_b32_e32 v132, 16, v3
	v_lshl_add_u64 v[4:5], v[0:1], 0, v[132:133]
	v_or_b32_e32 v1, s1, v175
	v_cmp_gt_u32_e32 vcc, 16, v174
	v_lshl_add_u64 v[4:5], s[82:83], 0, v[4:5]
	s_mov_b64 s[14:15], 0x16000000
	v_lshl_or_b32 v132, v1, 1, v0
	v_cndmask_b32_e64 v124, 0, 1.0, vcc
	v_lshl_add_u64 v[144:145], v[4:5], 0, s[14:15]
	v_lshl_add_u64 v[4:5], s[82:83], 0, v[132:133]
	v_or_b32_e32 v132, v0, v3
	v_xor_b32_e32 v128, 0x80000000, v124
	v_mul_i32_i24_e32 v7, 0xffffff74, v173
	v_mul_u32_u24_e32 v9, 0x90, v174
	v_lshl_add_u64 v[146:147], v[4:5], 0, s[14:15]
	v_lshl_add_u64 v[4:5], s[82:83], 0, v[132:133]
	s_mov_b32 s5, 0
	v_mov_b32_e32 v125, v124
	v_mov_b32_e32 v126, v124
	v_mov_b32_e32 v127, v124
	v_mov_b32_e32 v129, v128
	v_mov_b32_e32 v130, v128
	v_mov_b32_e32 v131, v128
	v_or_b32_e32 v180, v177, v176
	s_lshl_b32 s7, s84, 2
	s_lshl_b32 s11, s84, 5
	v_or_b32_e32 v182, 32, v174
	s_add_i32 s12, s3, s0
	v_lshl_add_u64 v[148:149], v[4:5], 0, s[14:15]
	v_lshlrev_b32_e32 v183, 2, v0
	v_add_u32_e32 v184, v6, v9
	v_add_u32_e32 v185, v178, v7
	v_add_u32_e32 v186, v8, v2

.LBB0_566:
	s_setprio 0
	s_mov_b64 s[0:1], 0
